# P8 epilogue sample rows: all four carried-state loads in flight together; P2 epilogue sample rows: state lines touched up front
# speedup vs baseline: 1.0139x; 1.0139x over previous
; __device__ __forceinline__ unsigned cvt_pk_bf16(float lo, float hi) { unsigned r; asm volatile("v_cvt_pk_bf16_f32 %0, %1, %2" : "=v"(r) : "v"(lo), "v"(hi)); return r; }
;     __device__ __forceinline__ void operator()(const f32x4 (&acc)[2][2][4][2], const Unit& u, int wr, int wc, int fr, int fq) const {
;     ...
;             if (u.pm == 64 && ai == 1) {
; #pragma unroll
;                 for (int m = 0; m < 4; ++m) { const int r = rbase + HALF + 16 * m, sb = r - MP;
;                     const f32x4 z2 = *(const f32x4*)(st + (size_t)(sb * 2) * D + xch), z1 = *(const f32x4*)(st + (size_t)(sb * 2 + 1) * D + xch);
;                     const f32x4 ua = acc[1][0][m][0] * (w0 * z2 + w1 * z1 + w2 * z[m]), ma = acc[1][1][m][1] + bm;
;                     bf16_t* rowp = O + (size_t)r * DP + xch;
;                     u32x2 a; a.x = cvt_pk_bf16(ua[0], ua[1]); a.y = cvt_pk_bf16(ua[2], ua[3]); *(u32x2*)(rowp + C_UA) = a;
;                     u32x2 g; g.x = cvt_pk_bf16(ma[0], ma[1]); g.y = cvt_pk_bf16(ma[2], ma[3]); *(u32x2*)(rowp + C_MA) = g;
;                     *(f32x4*)(outs + (size_t)(sb * 2) * D + xch) = z1; *(f32x4*)(outs + (size_t)(sb * 2 + 1) * D + xch) = z[m]; }
.LBB0_198:
	v_lshlrev_b32_e32 v0, 1, v182
	v_add_u32_e32 v180, 0xffff7f00, v0
	v_ashrrev_i32_e32 v181, 31, v180
	v_lshlrev_b64 v[200:201], 12, v[180:181]
	v_lshl_add_u64 v[180:181], s[74:75], 0, v[200:201]
	v_lshl_add_u64 v[180:181], v[180:181], 0, v[178:179]
	s_mov_b64 s[98:99], 0x1000
	v_lshl_add_u64 v[238:239], v[180:181], 0, s[98:99]
	global_load_dword v230, v[238:239], off
	s_mov_b64 s[98:99], 0x20000
	v_lshl_add_u64 v[238:239], v[180:181], 0, s[98:99]
	global_load_dword v231, v[238:239], off
	s_mov_b64 s[98:99], 0x21000
	v_lshl_add_u64 v[238:239], v[180:181], 0, s[98:99]
	global_load_dword v232, v[238:239], off
	s_mov_b64 s[98:99], 0x40000
	v_lshl_add_u64 v[238:239], v[180:181], 0, s[98:99]
	global_load_dword v233, v[238:239], off
	s_mov_b64 s[98:99], 0x41000
	v_lshl_add_u64 v[238:239], v[180:181], 0, s[98:99]
	global_load_dword v234, v[238:239], off
	s_mov_b64 s[98:99], 0x60000
	v_lshl_add_u64 v[238:239], v[180:181], 0, s[98:99]
	global_load_dword v235, v[238:239], off
	s_mov_b64 s[98:99], 0x61000
	v_lshl_add_u64 v[238:239], v[180:181], 0, s[98:99]
	global_load_dword v236, v[238:239], off
	global_load_dwordx4 v[192:195], v[180:181], off
	v_add_u32_e32 v180, 0xffff7f01, v0
	v_ashrrev_i32_e32 v181, 31, v180
	v_lshlrev_b64 v[202:203], 12, v[180:181]
	v_lshl_add_u64 v[180:181], s[74:75], 0, v[202:203]
	v_lshl_add_u64 v[180:181], v[180:181], 0, v[178:179]
	global_load_dwordx4 v[196:199], v[180:181], off
	v_pk_add_f32 v[226:227], v[46:47], v[130:131]
	v_add_u32_e32 v0, 0x90, v190
	v_lshlrev_b32_e32 v191, 1, v0
	s_or_b64 s[14:15], s[14:15], exec
	s_waitcnt vmcnt(0)
	v_pk_mul_f32 v[180:181], v[144:145], v[198:199]
	v_pk_mul_f32 v[224:225], v[142:143], v[196:197]
	v_pk_fma_f32 v[180:181], v[136:137], v[194:195], v[180:181]
	v_pk_fma_f32 v[192:193], v[134:135], v[192:193], v[224:225]
	v_pk_fma_f32 v[180:181], v[160:161], v[140:141], v[180:181]
	v_pk_fma_f32 v[192:193], v[158:159], v[138:139], v[192:193]
	v_pk_mul_f32 v[194:195], v[64:65], v[180:181]
	v_mov_b64_e32 v[180:181], s[64:65]
	v_pk_mul_f32 v[192:193], v[62:63], v[192:193]
	v_mad_i64_i32 v[228:229], s[12:13], v182, s33, v[180:181]
	v_lshlrev_b64 v[182:183], 1, v[176:177]
	v_lshl_add_u64 v[228:229], v[228:229], 0, v[182:183]
	v_cvt_pk_bf16_f32 v192, v192, v193
	v_cvt_pk_bf16_f32 v193, v194, v195
	v_pk_add_f32 v[224:225], v[48:49], v[132:133]
	global_store_dwordx2 v[228:229], v[192:193], off
	v_cvt_pk_bf16_f32 v192, v226, v227
	v_cvt_pk_bf16_f32 v193, v224, v225
	global_store_dwordx2 v[228:229], v[192:193], off offset:2048
	v_lshl_add_u64 v[192:193], s[78:79], 0, v[200:201]
	v_lshl_add_u64 v[192:193], v[192:193], 0, v[178:179]
	global_store_dwordx4 v[192:193], v[196:199], off
	v_lshl_add_u64 v[192:193], s[78:79], 0, v[202:203]
	v_lshl_add_u64 v[192:193], v[192:193], 0, v[178:179]
	global_store_dwordx4 v[192:193], v[158:161], off
	v_add_u32_e32 v192, 0xffff7f01, v191
	v_ashrrev_i32_e32 v193, 31, v192
	v_add_u32_e32 v158, 0xffff7f00, v191
	v_ashrrev_i32_e32 v159, 31, v158
	v_lshlrev_b64 v[196:197], 12, v[158:159]
	v_lshlrev_b64 v[198:199], 12, v[192:193]
	v_lshl_add_u64 v[158:159], s[74:75], 0, v[196:197]
	v_lshl_add_u64 v[192:193], s[74:75], 0, v[198:199]
	v_lshl_add_u64 v[158:159], v[158:159], 0, v[178:179]
	v_lshl_add_u64 v[192:193], v[192:193], 0, v[178:179]
	global_load_dwordx4 v[158:161], v[158:159], off
	v_mad_i64_i32 v[224:225], s[12:13], v0, s33, v[180:181]
	global_load_dwordx4 v[192:195], v[192:193], off
	v_lshl_add_u64 v[224:225], v[224:225], 0, v[182:183]
	v_add_u32_e32 v0, 0xa0, v190
	s_waitcnt vmcnt(0)
; __device__ __forceinline__ unsigned cvt_pk_bf16(float lo, float hi) { unsigned r; asm volatile("v_cvt_pk_bf16_f32 %0, %1, %2" : "=v"(r) : "v"(lo), "v"(hi)); return r; }
;     __device__ __forceinline__ void operator()(const f32x4 (&acc)[2][2][4][2], const Unit& u, int wr, int wc, int fr, int fq) const {
;     ...
;                 for (int m = 0; m < 4; ++m) { const int r = rbase + HALF + 16 * m, sb = r - MP;
;                     const f32x4 z2 = *(const f32x4*)(st + (size_t)(sb * 2) * D + xch), z1 = *(const f32x4*)(st + (size_t)(sb * 2 + 1) * D + xch);
;                     const f32x4 ua = acc[1][0][m][0] * (w0 * z2 + w1 * z1 + w2 * z[m]), ma = acc[1][1][m][1] + bm;
;                     bf16_t* rowp = O + (size_t)r * DP + xch;
;                     u32x2 a; a.x = cvt_pk_bf16(ua[0], ua[1]); a.y = cvt_pk_bf16(ua[2], ua[3]); *(u32x2*)(rowp + C_UA) = a;
;                     u32x2 g; g.x = cvt_pk_bf16(ma[0], ma[1]); g.y = cvt_pk_bf16(ma[2], ma[3]); *(u32x2*)(rowp + C_MA) = g;
;                     *(f32x4*)(outs + (size_t)(sb * 2) * D + xch) = z1; *(f32x4*)(outs + (size_t)(sb * 2 + 1) * D + xch) = z[m]; }
	v_pk_mul_f32 v[202:203], v[142:143], v[192:193]
	v_pk_mul_f32 v[200:201], v[144:145], v[194:195]
	v_pk_fma_f32 v[158:159], v[134:135], v[158:159], v[202:203]
	v_pk_fma_f32 v[160:161], v[136:137], v[160:161], v[200:201]
	v_pk_fma_f32 v[158:159], v[154:155], v[138:139], v[158:159]
	v_pk_fma_f32 v[160:161], v[156:157], v[140:141], v[160:161]
	v_pk_mul_f32 v[158:159], v[50:51], v[158:159]
	v_pk_mul_f32 v[160:161], v[52:53], v[160:161]
	v_cvt_pk_bf16_f32 v158, v158, v159
	v_pk_add_f32 v[200:201], v[32:33], v[132:133]
	v_cvt_pk_bf16_f32 v159, v160, v161
	v_pk_add_f32 v[202:203], v[30:31], v[130:131]
	global_store_dwordx2 v[224:225], v[158:159], off
	v_cvt_pk_bf16_f32 v158, v202, v203
	v_cvt_pk_bf16_f32 v159, v200, v201
	global_store_dwordx2 v[224:225], v[158:159], off offset:2048
	v_lshl_add_u64 v[158:159], s[78:79], 0, v[196:197]
	v_lshl_add_u64 v[158:159], v[158:159], 0, v[178:179]
	global_store_dwordx4 v[158:159], v[192:195], off
	v_lshl_add_u64 v[158:159], s[78:79], 0, v[198:199]
	v_lshl_add_u64 v[158:159], v[158:159], 0, v[178:179]
	global_store_dwordx4 v[158:159], v[154:157], off
	v_lshlrev_b32_e32 v158, 1, v0
	v_mad_i64_i32 v[200:201], s[12:13], v0, s33, v[180:181]
	v_add_u32_e32 v154, 0xffff7f00, v158
	v_add_u32_e32 v158, 0xffff7f01, v158
	v_ashrrev_i32_e32 v155, 31, v154
	v_ashrrev_i32_e32 v159, 31, v158
	v_lshlrev_b64 v[192:193], 12, v[154:155]
	v_lshlrev_b64 v[194:195], 12, v[158:159]
	v_lshl_add_u64 v[154:155], s[74:75], 0, v[192:193]
	v_lshl_add_u64 v[158:159], s[74:75], 0, v[194:195]
	v_lshl_add_u64 v[154:155], v[154:155], 0, v[178:179]
	v_lshl_add_u64 v[158:159], v[158:159], 0, v[178:179]
	global_load_dwordx4 v[154:157], v[154:155], off
	v_lshl_add_u64 v[200:201], v[200:201], 0, v[182:183]
	global_load_dwordx4 v[158:161], v[158:159], off
	v_add_u32_e32 v0, 0xb0, v190
	s_waitcnt vmcnt(0)
	v_pk_mul_f32 v[198:199], v[142:143], v[158:159]
	v_pk_mul_f32 v[196:197], v[144:145], v[160:161]
	v_pk_fma_f32 v[154:155], v[134:135], v[154:155], v[198:199]
	v_pk_fma_f32 v[156:157], v[136:137], v[156:157], v[196:197]
	v_pk_fma_f32 v[154:155], v[150:151], v[138:139], v[154:155]
	v_pk_fma_f32 v[156:157], v[152:153], v[140:141], v[156:157]
	v_pk_mul_f32 v[154:155], v[34:35], v[154:155]
	v_pk_mul_f32 v[156:157], v[36:37], v[156:157]
	v_cvt_pk_bf16_f32 v154, v154, v155
	v_pk_add_f32 v[196:197], v[16:17], v[132:133]
	v_cvt_pk_bf16_f32 v155, v156, v157
	v_pk_add_f32 v[198:199], v[14:15], v[130:131]
	global_store_dwordx2 v[200:201], v[154:155], off
	v_cvt_pk_bf16_f32 v154, v198, v199
	v_cvt_pk_bf16_f32 v155, v196, v197
	global_store_dwordx2 v[200:201], v[154:155], off offset:2048
	v_lshl_add_u64 v[154:155], s[78:79], 0, v[192:193]
	v_lshl_add_u64 v[154:155], v[154:155], 0, v[178:179]
	global_store_dwordx4 v[154:155], v[158:161], off
	v_lshl_add_u64 v[154:155], s[78:79], 0, v[194:195]
	v_lshl_add_u64 v[154:155], v[154:155], 0, v[178:179]
	global_store_dwordx4 v[154:155], v[150:153], off
	v_lshlrev_b32_e32 v154, 1, v0
	v_pk_add_f32 v[130:131], v[2:3], v[130:131]
	v_add_u32_e32 v150, 0xffff7f00, v154
	v_add_u32_e32 v154, 0xffff7f01, v154
	v_ashrrev_i32_e32 v151, 31, v150
	v_ashrrev_i32_e32 v155, 31, v154
	v_lshlrev_b64 v[158:159], 12, v[150:151]
	v_lshlrev_b64 v[160:161], 12, v[154:155]
	v_lshl_add_u64 v[150:151], s[74:75], 0, v[158:159]
	v_lshl_add_u64 v[154:155], s[74:75], 0, v[160:161]
	v_lshl_add_u64 v[150:151], v[150:151], 0, v[178:179]
	v_lshl_add_u64 v[154:155], v[154:155], 0, v[178:179]
	global_load_dwordx4 v[150:153], v[150:151], off
	v_pk_add_f32 v[132:133], v[4:5], v[132:133]
	global_load_dwordx4 v[154:157], v[154:155], off
	s_waitcnt vmcnt(0)
	v_pk_mul_f32 v[142:143], v[142:143], v[154:155]
	v_pk_mul_f32 v[144:145], v[144:145], v[156:157]
	v_pk_fma_f32 v[134:135], v[134:135], v[150:151], v[142:143]
	v_pk_fma_f32 v[136:137], v[136:137], v[152:153], v[144:145]
	v_pk_fma_f32 v[134:135], v[146:147], v[138:139], v[134:135]
	v_mad_i64_i32 v[138:139], s[12:13], v0, s33, v[180:181]
	v_pk_fma_f32 v[136:137], v[148:149], v[140:141], v[136:137]
	v_pk_mul_f32 v[134:135], v[18:19], v[134:135]
	v_lshl_add_u64 v[138:139], v[138:139], 0, v[182:183]
	v_pk_mul_f32 v[136:137], v[20:21], v[136:137]
	v_cvt_pk_bf16_f32 v134, v134, v135
	v_lshl_add_u64 v[180:181], s[78:79], 0, v[160:161]
	v_cvt_pk_bf16_f32 v135, v136, v137
	global_store_dwordx2 v[138:139], v[134:135], off
	v_cvt_pk_bf16_f32 v130, v130, v131
	v_cvt_pk_bf16_f32 v131, v132, v133
	global_store_dwordx2 v[138:139], v[130:131], off offset:2048
	v_lshl_add_u64 v[130:131], s[78:79], 0, v[158:159]
	v_lshl_add_u64 v[130:131], v[130:131], 0, v[178:179]
	global_store_dwordx4 v[130:131], v[154:157], off

; __device__ __forceinline__ u32x4 pack8(const float (&f)[8]) { u32x4 o; o.x = cvt_pk_bf16(f[0], f[1]); o.y = cvt_pk_bf16(f[2], f[3]); o.z = cvt_pk_bf16(f[4], f[5]); o.w = cvt_pk_bf16(f[6], f[7]); return o; }
; __device__ __forceinline__ float sigmoidf_(float x) { return __builtin_amdgcn_rcpf(1.0f + __expf(-x)); }
;     __device__ __forceinline__ void operator()(const f32x4 (&acc)[2][2][4][2], const Unit& u, int wr, int wc, int fr, int fq) const {
;     ...
;             if (u.pm == 64 && ai == 1) {
; #pragma unroll
;                 for (int m = 0; m < 4; ++m) { const int r = rbase + HALF + 16 * m, sb = r - MP;
;                     float u2[8], u1[8], o[8], uu[8]; load8f(st + (size_t)(sb * 2) * DFF + ch0, u2); load8f(st + (size_t)(sb * 2 + 1) * DFF + ch0, u1);
; #pragma unroll
;                     for (int k = 0; k < 8; ++k) { const float x = acc[1][0][m][k >> 2][k & 3], g = acc[1][1][m][k >> 2][k & 3]; uu[k] = x;
;                         const float uc = w0[k] * u2[k] + w1[k] * u1[k] + w2[k] * x + bb[k]; o[k] = uc * sigmoidf_(uc) * g; }
;                     *(u32x4*)(ACT + (size_t)r * DFF + ch0) = pack8(o);
;                     store8f(outs + (size_t)(sb * 2) * DFF + ch0, u1); store8f(outs + (size_t)(sb * 2 + 1) * DFF + ch0, uu); }
.Lp8e_smp_10:
	s_add_i32 s10, s18, 0
	s_mul_i32 s10, s10, 0x5800
	s_add_u32 s94, s70, s10
	s_addc_u32 s95, s71, 0
	s_add_u32 s98, s94, 0x2c00
	s_addc_u32 s99, s95, 0
	global_load_dwordx4 v[98:101], v248, s[94:95]
	global_load_dwordx4 v[102:105], v248, s[94:95] offset:16
	global_load_dwordx4 v[106:109], v248, s[98:99]
	global_load_dwordx4 v[110:113], v248, s[98:99] offset:16
	s_add_i32 s10, s18, 16
	s_mul_i32 s10, s10, 0x5800
	s_add_u32 s94, s70, s10
	s_addc_u32 s95, s71, 0
	s_add_u32 s98, s94, 0x2c00
	s_addc_u32 s99, s95, 0
	global_load_dwordx4 v[114:117], v248, s[94:95]
	global_load_dwordx4 v[118:121], v248, s[94:95] offset:16
	global_load_dwordx4 v[122:125], v248, s[98:99]
	global_load_dwordx4 v[126:129], v248, s[98:99] offset:16
	s_add_i32 s10, s18, 32
	s_mul_i32 s10, s10, 0x5800
	s_add_u32 s94, s70, s10
	s_addc_u32 s95, s71, 0
	s_add_u32 s98, s94, 0x2c00
	s_addc_u32 s99, s95, 0
	global_load_dwordx4 v[130:133], v248, s[94:95]
	global_load_dwordx4 v[134:137], v248, s[94:95] offset:16
	global_load_dwordx4 v[138:141], v248, s[98:99]
	global_load_dwordx4 v[142:145], v248, s[98:99] offset:16
	s_add_i32 s10, s18, 48
	s_mul_i32 s10, s10, 0x5800
	s_add_u32 s94, s70, s10
	s_addc_u32 s95, s71, 0
	s_add_u32 s98, s94, 0x2c00
	s_addc_u32 s99, s95, 0
	global_load_dwordx4 v[146:149], v248, s[94:95]
	global_load_dwordx4 v[150:153], v248, s[94:95] offset:16
	global_load_dwordx4 v[154:157], v248, s[98:99]
	global_load_dwordx4 v[158:161], v248, s[98:99] offset:16
	s_add_i32 s55, s91, 128
	s_mul_i32 s10, s55, 0x1600
	s_add_u32 s92, s60, s10
	s_addc_u32 s93, s61, 0
	s_add_i32 s10, s18, 0
	s_mul_i32 s10, s10, 0x5800
	s_add_u32 s94, s74, s10
	s_addc_u32 s95, s75, 0
	s_add_u32 s98, s94, 0x2c00
	s_addc_u32 s99, s95, 0
	v_fma_f32 v184, v66, v90, v74
	v_fma_f32 v185, v67, v91, v75
	v_fma_f32 v186, v68, v92, v76
	v_fma_f32 v187, v69, v93, v77
	v_fma_f32 v188, v70, v86, v78
	v_fma_f32 v189, v71, v87, v79
	v_fma_f32 v190, v72, v88, v80
	v_fma_f32 v191, v73, v89, v81
	s_waitcnt vmcnt(12)
	v_fmac_f32_e32 v184, v58, v106
	v_fmac_f32_e32 v185, v59, v107
	v_fmac_f32_e32 v186, v60, v108
	v_fmac_f32_e32 v187, v61, v109
	v_fmac_f32_e32 v188, v62, v110
	v_fmac_f32_e32 v189, v63, v111
	v_fmac_f32_e32 v190, v64, v112
	v_fmac_f32_e32 v191, v65, v113
	v_fmac_f32_e32 v184, v50, v98
	v_fmac_f32_e32 v185, v51, v99
	v_fmac_f32_e32 v186, v52, v100
	v_fmac_f32_e32 v187, v53, v101
	v_fmac_f32_e32 v188, v54, v102
	v_fmac_f32_e32 v189, v55, v103
	v_fmac_f32_e32 v190, v56, v104
	v_fmac_f32_e32 v191, v57, v105
	v_mul_f32_e32 v192, 0xbfb8aa3b, v184
	v_mul_f32_e32 v193, 0xbfb8aa3b, v185
	v_mul_f32_e32 v194, 0xbfb8aa3b, v186
	v_mul_f32_e32 v195, 0xbfb8aa3b, v187
	v_mul_f32_e32 v196, 0xbfb8aa3b, v188
	v_mul_f32_e32 v197, 0xbfb8aa3b, v189
	v_mul_f32_e32 v198, 0xbfb8aa3b, v190
	v_mul_f32_e32 v199, 0xbfb8aa3b, v191
	v_exp_f32_e32 v192, v192
	v_exp_f32_e32 v193, v193
	v_exp_f32_e32 v194, v194
	v_exp_f32_e32 v195, v195
	v_exp_f32_e32 v196, v196
	v_exp_f32_e32 v197, v197
	v_exp_f32_e32 v198, v198
	v_exp_f32_e32 v199, v199
	v_add_f32_e32 v192, 1.0, v192
	v_add_f32_e32 v193, 1.0, v193
	v_add_f32_e32 v194, 1.0, v194
	v_add_f32_e32 v195, 1.0, v195
	v_add_f32_e32 v196, 1.0, v196
	v_add_f32_e32 v197, 1.0, v197
	v_add_f32_e32 v198, 1.0, v198
	v_add_f32_e32 v199, 1.0, v199
	v_rcp_f32_e32 v192, v192
	v_rcp_f32_e32 v193, v193
	v_rcp_f32_e32 v194, v194
	v_rcp_f32_e32 v195, v195
	v_rcp_f32_e32 v196, v196
	v_rcp_f32_e32 v197, v197
	v_rcp_f32_e32 v198, v198
	v_rcp_f32_e32 v199, v199
	v_mul_f32_e32 v184, v184, v192
	v_mul_f32_e32 v185, v185, v193
	v_mul_f32_e32 v186, v186, v194
	v_mul_f32_e32 v187, v187, v195
	v_mul_f32_e32 v188, v188, v196
	v_mul_f32_e32 v189, v189, v197
	v_mul_f32_e32 v190, v190, v198
	v_mul_f32_e32 v191, v191, v199
	v_mul_f32_e32 v184, v94, v184
	v_mul_f32_e32 v185, v95, v185
	v_mul_f32_e32 v186, v96, v186
	v_mul_f32_e32 v187, v97, v187
	v_mul_f32_e32 v188, v82, v188
	v_mul_f32_e32 v189, v83, v189
	v_mul_f32_e32 v190, v84, v190
	v_mul_f32_e32 v191, v85, v191
	v_cvt_pk_bf16_f32 v200, v184, v185
	v_cvt_pk_bf16_f32 v201, v186, v187
	v_cvt_pk_bf16_f32 v202, v188, v189
	v_cvt_pk_bf16_f32 v203, v190, v191
	global_store_dwordx4 v183, v[200:203], s[92:93]
	global_store_dwordx4 v248, v[106:109], s[94:95]
	global_store_dwordx4 v248, v[110:113], s[94:95] offset:16
	global_store_dwordx4 v248, v[90:93], s[98:99]
	global_store_dwordx4 v248, v[86:89], s[98:99] offset:16
	s_nop 1

; __device__ __forceinline__ u32x4 pack8(const float (&f)[8]) { u32x4 o; o.x = cvt_pk_bf16(f[0], f[1]); o.y = cvt_pk_bf16(f[2], f[3]); o.z = cvt_pk_bf16(f[4], f[5]); o.w = cvt_pk_bf16(f[6], f[7]); return o; }
; __device__ __forceinline__ float sigmoidf_(float x) { return __builtin_amdgcn_rcpf(1.0f + __expf(-x)); }
;     __device__ __forceinline__ void operator()(const f32x4 (&acc)[2][2][4][2], const Unit& u, int wr, int wc, int fr, int fq) const {
;     ...
;             if (u.pm == 64 && ai == 1) {
; #pragma unroll
;                 for (int m = 0; m < 4; ++m) { const int r = rbase + HALF + 16 * m, sb = r - MP;
;                     float u2[8], u1[8], o[8], uu[8]; load8f(st + (size_t)(sb * 2) * DFF + ch0, u2); load8f(st + (size_t)(sb * 2 + 1) * DFF + ch0, u1);
; #pragma unroll
;                     for (int k = 0; k < 8; ++k) { const float x = acc[1][0][m][k >> 2][k & 3], g = acc[1][1][m][k >> 2][k & 3]; uu[k] = x;
;                         const float uc = w0[k] * u2[k] + w1[k] * u1[k] + w2[k] * x + bb[k]; o[k] = uc * sigmoidf_(uc) * g; }
;                     *(u32x4*)(ACT + (size_t)r * DFF + ch0) = pack8(o);
;                     store8f(outs + (size_t)(sb * 2) * DFF + ch0, u1); store8f(outs + (size_t)(sb * 2 + 1) * DFF + ch0, uu); }
.Lp8e_smp_11:
	s_add_i32 s55, s91, 144
	s_mul_i32 s10, s55, 0x1600
	s_add_u32 s92, s60, s10
	s_addc_u32 s93, s61, 0
	s_add_i32 s10, s18, 16
	s_mul_i32 s10, s10, 0x5800
	s_add_u32 s94, s74, s10
	s_addc_u32 s95, s75, 0
	s_add_u32 s98, s94, 0x2c00
	s_addc_u32 s99, s95, 0
	v_fma_f32 v184, v66, v42, v74
	v_fma_f32 v185, v67, v43, v75
	v_fma_f32 v186, v68, v44, v76
	v_fma_f32 v187, v69, v45, v77
	v_fma_f32 v188, v70, v38, v78
	v_fma_f32 v189, v71, v39, v79
	v_fma_f32 v190, v72, v40, v80
	v_fma_f32 v191, v73, v41, v81
	s_waitcnt vmcnt(13)
	v_fmac_f32_e32 v184, v58, v122
	v_fmac_f32_e32 v185, v59, v123
	v_fmac_f32_e32 v186, v60, v124
	v_fmac_f32_e32 v187, v61, v125
	v_fmac_f32_e32 v188, v62, v126
	v_fmac_f32_e32 v189, v63, v127
	v_fmac_f32_e32 v190, v64, v128
	v_fmac_f32_e32 v191, v65, v129
	v_fmac_f32_e32 v184, v50, v114
	v_fmac_f32_e32 v185, v51, v115
	v_fmac_f32_e32 v186, v52, v116
	v_fmac_f32_e32 v187, v53, v117
	v_fmac_f32_e32 v188, v54, v118
	v_fmac_f32_e32 v189, v55, v119
	v_fmac_f32_e32 v190, v56, v120
	v_fmac_f32_e32 v191, v57, v121
	v_mul_f32_e32 v192, 0xbfb8aa3b, v184
	v_mul_f32_e32 v193, 0xbfb8aa3b, v185
	v_mul_f32_e32 v194, 0xbfb8aa3b, v186
	v_mul_f32_e32 v195, 0xbfb8aa3b, v187
	v_mul_f32_e32 v196, 0xbfb8aa3b, v188
	v_mul_f32_e32 v197, 0xbfb8aa3b, v189
	v_mul_f32_e32 v198, 0xbfb8aa3b, v190
	v_mul_f32_e32 v199, 0xbfb8aa3b, v191
	v_exp_f32_e32 v192, v192
	v_exp_f32_e32 v193, v193
	v_exp_f32_e32 v194, v194
	v_exp_f32_e32 v195, v195
	v_exp_f32_e32 v196, v196
	v_exp_f32_e32 v197, v197
	v_exp_f32_e32 v198, v198
	v_exp_f32_e32 v199, v199
	v_add_f32_e32 v192, 1.0, v192
	v_add_f32_e32 v193, 1.0, v193
	v_add_f32_e32 v194, 1.0, v194
	v_add_f32_e32 v195, 1.0, v195
	v_add_f32_e32 v196, 1.0, v196
	v_add_f32_e32 v197, 1.0, v197
	v_add_f32_e32 v198, 1.0, v198
	v_add_f32_e32 v199, 1.0, v199
	v_rcp_f32_e32 v192, v192
	v_rcp_f32_e32 v193, v193
	v_rcp_f32_e32 v194, v194
	v_rcp_f32_e32 v195, v195
	v_rcp_f32_e32 v196, v196
	v_rcp_f32_e32 v197, v197
	v_rcp_f32_e32 v198, v198
	v_rcp_f32_e32 v199, v199
	v_mul_f32_e32 v184, v184, v192
	v_mul_f32_e32 v185, v185, v193
	v_mul_f32_e32 v186, v186, v194
	v_mul_f32_e32 v187, v187, v195
	v_mul_f32_e32 v188, v188, v196
	v_mul_f32_e32 v189, v189, v197
	v_mul_f32_e32 v190, v190, v198
	v_mul_f32_e32 v191, v191, v199
	v_mul_f32_e32 v184, v46, v184
	v_mul_f32_e32 v185, v47, v185
	v_mul_f32_e32 v186, v48, v186
	v_mul_f32_e32 v187, v49, v187
	v_mul_f32_e32 v188, v34, v188
	v_mul_f32_e32 v189, v35, v189
	v_mul_f32_e32 v190, v36, v190
	v_mul_f32_e32 v191, v37, v191
	v_cvt_pk_bf16_f32 v224, v184, v185
	v_cvt_pk_bf16_f32 v225, v186, v187
	v_cvt_pk_bf16_f32 v226, v188, v189
	v_cvt_pk_bf16_f32 v227, v190, v191
	global_store_dwordx4 v183, v[224:227], s[92:93]
	global_store_dwordx4 v248, v[122:125], s[94:95]
	global_store_dwordx4 v248, v[126:129], s[94:95] offset:16
	global_store_dwordx4 v248, v[42:45], s[98:99]
	global_store_dwordx4 v248, v[38:41], s[98:99] offset:16
	s_nop 1

; __device__ __forceinline__ u32x4 pack8(const float (&f)[8]) { u32x4 o; o.x = cvt_pk_bf16(f[0], f[1]); o.y = cvt_pk_bf16(f[2], f[3]); o.z = cvt_pk_bf16(f[4], f[5]); o.w = cvt_pk_bf16(f[6], f[7]); return o; }
; __device__ __forceinline__ float sigmoidf_(float x) { return __builtin_amdgcn_rcpf(1.0f + __expf(-x)); }
;     __device__ __forceinline__ void operator()(const f32x4 (&acc)[2][2][4][2], const Unit& u, int wr, int wc, int fr, int fq) const {
;     ...
;             if (u.pm == 64 && ai == 1) {
; #pragma unroll
;                 for (int m = 0; m < 4; ++m) { const int r = rbase + HALF + 16 * m, sb = r - MP;
;                     float u2[8], u1[8], o[8], uu[8]; load8f(st + (size_t)(sb * 2) * DFF + ch0, u2); load8f(st + (size_t)(sb * 2 + 1) * DFF + ch0, u1);
; #pragma unroll
;                     for (int k = 0; k < 8; ++k) { const float x = acc[1][0][m][k >> 2][k & 3], g = acc[1][1][m][k >> 2][k & 3]; uu[k] = x;
;                         const float uc = w0[k] * u2[k] + w1[k] * u1[k] + w2[k] * x + bb[k]; o[k] = uc * sigmoidf_(uc) * g; }
;                     *(u32x4*)(ACT + (size_t)r * DFF + ch0) = pack8(o);
;                     store8f(outs + (size_t)(sb * 2) * DFF + ch0, u1); store8f(outs + (size_t)(sb * 2 + 1) * DFF + ch0, uu); }
.Lp8e_smp_12:
	s_add_i32 s55, s91, 160
	s_mul_i32 s10, s55, 0x1600
	s_add_u32 s92, s60, s10
	s_addc_u32 s93, s61, 0
	s_add_i32 s10, s18, 32
	s_mul_i32 s10, s10, 0x5800
	s_add_u32 s94, s74, s10
	s_addc_u32 s95, s75, 0
	s_add_u32 s98, s94, 0x2c00
	s_addc_u32 s99, s95, 0
	v_fma_f32 v184, v66, v26, v74
	v_fma_f32 v185, v67, v27, v75
	v_fma_f32 v186, v68, v28, v76
	v_fma_f32 v187, v69, v29, v77
	v_fma_f32 v188, v70, v22, v78
	v_fma_f32 v189, v71, v23, v79
	v_fma_f32 v190, v72, v24, v80
	v_fma_f32 v191, v73, v25, v81
	s_waitcnt vmcnt(14)
	v_fmac_f32_e32 v184, v58, v138
	v_fmac_f32_e32 v185, v59, v139
	v_fmac_f32_e32 v186, v60, v140
	v_fmac_f32_e32 v187, v61, v141
	v_fmac_f32_e32 v188, v62, v142
	v_fmac_f32_e32 v189, v63, v143
	v_fmac_f32_e32 v190, v64, v144
	v_fmac_f32_e32 v191, v65, v145
	v_fmac_f32_e32 v184, v50, v130
	v_fmac_f32_e32 v185, v51, v131
	v_fmac_f32_e32 v186, v52, v132
	v_fmac_f32_e32 v187, v53, v133
	v_fmac_f32_e32 v188, v54, v134
	v_fmac_f32_e32 v189, v55, v135
	v_fmac_f32_e32 v190, v56, v136
	v_fmac_f32_e32 v191, v57, v137
	v_mul_f32_e32 v192, 0xbfb8aa3b, v184
	v_mul_f32_e32 v193, 0xbfb8aa3b, v185
	v_mul_f32_e32 v194, 0xbfb8aa3b, v186
	v_mul_f32_e32 v195, 0xbfb8aa3b, v187
	v_mul_f32_e32 v196, 0xbfb8aa3b, v188
	v_mul_f32_e32 v197, 0xbfb8aa3b, v189
	v_mul_f32_e32 v198, 0xbfb8aa3b, v190
	v_mul_f32_e32 v199, 0xbfb8aa3b, v191
	v_exp_f32_e32 v192, v192
	v_exp_f32_e32 v193, v193
	v_exp_f32_e32 v194, v194
	v_exp_f32_e32 v195, v195
	v_exp_f32_e32 v196, v196
	v_exp_f32_e32 v197, v197
	v_exp_f32_e32 v198, v198
	v_exp_f32_e32 v199, v199
	v_add_f32_e32 v192, 1.0, v192
	v_add_f32_e32 v193, 1.0, v193
	v_add_f32_e32 v194, 1.0, v194
	v_add_f32_e32 v195, 1.0, v195
	v_add_f32_e32 v196, 1.0, v196
	v_add_f32_e32 v197, 1.0, v197
	v_add_f32_e32 v198, 1.0, v198
	v_add_f32_e32 v199, 1.0, v199
	v_rcp_f32_e32 v192, v192
	v_rcp_f32_e32 v193, v193
	v_rcp_f32_e32 v194, v194
	v_rcp_f32_e32 v195, v195
	v_rcp_f32_e32 v196, v196
	v_rcp_f32_e32 v197, v197
	v_rcp_f32_e32 v198, v198
	v_rcp_f32_e32 v199, v199
	v_mul_f32_e32 v184, v184, v192
	v_mul_f32_e32 v185, v185, v193
	v_mul_f32_e32 v186, v186, v194
	v_mul_f32_e32 v187, v187, v195
	v_mul_f32_e32 v188, v188, v196
	v_mul_f32_e32 v189, v189, v197
	v_mul_f32_e32 v190, v190, v198
	v_mul_f32_e32 v191, v191, v199
	v_mul_f32_e32 v184, v30, v184
	v_mul_f32_e32 v185, v31, v185
	v_mul_f32_e32 v186, v32, v186
	v_mul_f32_e32 v187, v33, v187
	v_mul_f32_e32 v188, v18, v188
	v_mul_f32_e32 v189, v19, v189
	v_mul_f32_e32 v190, v20, v190
	v_mul_f32_e32 v191, v21, v191
	v_cvt_pk_bf16_f32 v200, v184, v185
	v_cvt_pk_bf16_f32 v201, v186, v187
	v_cvt_pk_bf16_f32 v202, v188, v189
	v_cvt_pk_bf16_f32 v203, v190, v191
	global_store_dwordx4 v183, v[200:203], s[92:93]
	global_store_dwordx4 v248, v[138:141], s[94:95]
	global_store_dwordx4 v248, v[142:145], s[94:95] offset:16
	global_store_dwordx4 v248, v[26:29], s[98:99]
	global_store_dwordx4 v248, v[22:25], s[98:99] offset:16
	s_nop 1

; __device__ __forceinline__ u32x4 pack8(const float (&f)[8]) { u32x4 o; o.x = cvt_pk_bf16(f[0], f[1]); o.y = cvt_pk_bf16(f[2], f[3]); o.z = cvt_pk_bf16(f[4], f[5]); o.w = cvt_pk_bf16(f[6], f[7]); return o; }
; __device__ __forceinline__ float sigmoidf_(float x) { return __builtin_amdgcn_rcpf(1.0f + __expf(-x)); }
;     __device__ __forceinline__ void operator()(const f32x4 (&acc)[2][2][4][2], const Unit& u, int wr, int wc, int fr, int fq) const {
;     ...
;             if (u.pm == 64 && ai == 1) {
; #pragma unroll
;                 for (int m = 0; m < 4; ++m) { const int r = rbase + HALF + 16 * m, sb = r - MP;
;                     float u2[8], u1[8], o[8], uu[8]; load8f(st + (size_t)(sb * 2) * DFF + ch0, u2); load8f(st + (size_t)(sb * 2 + 1) * DFF + ch0, u1);
; #pragma unroll
;                     for (int k = 0; k < 8; ++k) { const float x = acc[1][0][m][k >> 2][k & 3], g = acc[1][1][m][k >> 2][k & 3]; uu[k] = x;
;                         const float uc = w0[k] * u2[k] + w1[k] * u1[k] + w2[k] * x + bb[k]; o[k] = uc * sigmoidf_(uc) * g; }
;                     *(u32x4*)(ACT + (size_t)r * DFF + ch0) = pack8(o);
;                     store8f(outs + (size_t)(sb * 2) * DFF + ch0, u1); store8f(outs + (size_t)(sb * 2 + 1) * DFF + ch0, uu); }
.Lp8e_smp_13:
	s_add_i32 s55, s91, 176
	s_mul_i32 s10, s55, 0x1600
	s_add_u32 s92, s60, s10
	s_addc_u32 s93, s61, 0
	s_add_i32 s10, s18, 48
	s_mul_i32 s10, s10, 0x5800
	s_add_u32 s94, s74, s10
	s_addc_u32 s95, s75, 0
	s_add_u32 s98, s94, 0x2c00
	s_addc_u32 s99, s95, 0
	v_fma_f32 v184, v66, v10, v74
	v_fma_f32 v185, v67, v11, v75
	v_fma_f32 v186, v68, v12, v76
	v_fma_f32 v187, v69, v13, v77
	v_fma_f32 v188, v70, v6, v78
	v_fma_f32 v189, v71, v7, v79
	v_fma_f32 v190, v72, v8, v80
	v_fma_f32 v191, v73, v9, v81
	s_waitcnt vmcnt(15)
	v_fmac_f32_e32 v184, v58, v154
	v_fmac_f32_e32 v185, v59, v155
	v_fmac_f32_e32 v186, v60, v156
	v_fmac_f32_e32 v187, v61, v157
	v_fmac_f32_e32 v188, v62, v158
	v_fmac_f32_e32 v189, v63, v159
	v_fmac_f32_e32 v190, v64, v160
	v_fmac_f32_e32 v191, v65, v161
	v_fmac_f32_e32 v184, v50, v146
	v_fmac_f32_e32 v185, v51, v147
	v_fmac_f32_e32 v186, v52, v148
	v_fmac_f32_e32 v187, v53, v149
	v_fmac_f32_e32 v188, v54, v150
	v_fmac_f32_e32 v189, v55, v151
	v_fmac_f32_e32 v190, v56, v152
	v_fmac_f32_e32 v191, v57, v153
	v_mul_f32_e32 v192, 0xbfb8aa3b, v184
	v_mul_f32_e32 v193, 0xbfb8aa3b, v185
	v_mul_f32_e32 v194, 0xbfb8aa3b, v186
	v_mul_f32_e32 v195, 0xbfb8aa3b, v187
	v_mul_f32_e32 v196, 0xbfb8aa3b, v188
	v_mul_f32_e32 v197, 0xbfb8aa3b, v189
	v_mul_f32_e32 v198, 0xbfb8aa3b, v190
	v_mul_f32_e32 v199, 0xbfb8aa3b, v191
	v_exp_f32_e32 v192, v192
	v_exp_f32_e32 v193, v193
	v_exp_f32_e32 v194, v194
	v_exp_f32_e32 v195, v195
	v_exp_f32_e32 v196, v196
	v_exp_f32_e32 v197, v197
	v_exp_f32_e32 v198, v198
	v_exp_f32_e32 v199, v199
	v_add_f32_e32 v192, 1.0, v192
	v_add_f32_e32 v193, 1.0, v193
	v_add_f32_e32 v194, 1.0, v194
	v_add_f32_e32 v195, 1.0, v195
	v_add_f32_e32 v196, 1.0, v196
	v_add_f32_e32 v197, 1.0, v197
	v_add_f32_e32 v198, 1.0, v198
	v_add_f32_e32 v199, 1.0, v199
	v_rcp_f32_e32 v192, v192
	v_rcp_f32_e32 v193, v193
	v_rcp_f32_e32 v194, v194
	v_rcp_f32_e32 v195, v195
	v_rcp_f32_e32 v196, v196
	v_rcp_f32_e32 v197, v197
	v_rcp_f32_e32 v198, v198
	v_rcp_f32_e32 v199, v199
	v_mul_f32_e32 v184, v184, v192
	v_mul_f32_e32 v185, v185, v193
	v_mul_f32_e32 v186, v186, v194
	v_mul_f32_e32 v187, v187, v195
	v_mul_f32_e32 v188, v188, v196
	v_mul_f32_e32 v189, v189, v197
	v_mul_f32_e32 v190, v190, v198
	v_mul_f32_e32 v191, v191, v199
	v_mul_f32_e32 v184, v14, v184
	v_mul_f32_e32 v185, v15, v185
	v_mul_f32_e32 v186, v16, v186
	v_mul_f32_e32 v187, v17, v187
	v_mul_f32_e32 v188, v2, v188
	v_mul_f32_e32 v189, v3, v189
	v_mul_f32_e32 v190, v4, v190
	v_mul_f32_e32 v191, v5, v191
	v_cvt_pk_bf16_f32 v224, v184, v185
	v_cvt_pk_bf16_f32 v225, v186, v187
	v_cvt_pk_bf16_f32 v226, v188, v189
	v_cvt_pk_bf16_f32 v227, v190, v191
	global_store_dwordx4 v183, v[224:227], s[92:93]
	global_store_dwordx4 v248, v[154:157], s[94:95]
	global_store_dwordx4 v248, v[158:161], s[94:95] offset:16
	global_store_dwordx4 v248, v[10:13], s[98:99]
	global_store_dwordx4 v248, v[6:9], s[98:99] offset:16
	s_nop 1
